# GEMM epilogue lane shuffles (shift up by one lane) done with DPP row_shr:1 instead of ds_bpermute, on top of the combined version
# speedup vs baseline: 1.0058x; 1.0058x over previous
; #define LAS __attribute__((address_space(3)))
;     DEV bool operator()(f32x4 (&acc)[2][2][4][2], const Unit& u, int wr, int wc, int fr, int fq) const {
;         const int ch0 = u.pn * 128 + wc * 32 + 8 * fq;
;         float w[3][8];
; #pragma unroll
;         for (int k = 0; k < 3; ++k) { const f32x4 w0 = *(const f32x4*)(cw + k * DFF + ch0), w1 = *(const f32x4*)(cw + k * DFF + ch0 + 4);
; #pragma unroll
;             for (int j = 0; j < 4; ++j) { w[k][j] = w0[j]; w[k][4 + j] = w1[j]; } }
;         float p6[8], p7[8];
; #pragma unroll
;         for (int c = 0; c < 8; ++c) { p6[c] = __shfl_up(acc[1][0][2][c >> 2][c & 3], 1); p7[c] = __shfl_up(acc[1][0][3][c >> 2][c & 3], 1); }
;         LAS float* EX = (LAS float*)ex + (wc * 4 + fq) * 16;
;         if (wr == 0 && fr == 15) {
; #pragma unroll
;             for (int c = 0; c < 8; ++c) { EX[c] = acc[1][0][2][c >> 2][c & 3]; EX[8 + c] = acc[1][0][3][c >> 2][c & 3]; }
;         }
.LBB0_31:
	v_lshl_or_b32 v192, s20, 7, v229
	v_ashrrev_i32_e32 v193, 31, v192
	v_mov_b32_dpp v134, v246 row_newbcast:0 row_mask:0xf bank_mask:0xf
	v_mov_b32_dpp v135, v246 row_newbcast:1 row_mask:0xf bank_mask:0xf
	v_mov_b32_dpp v136, v246 row_newbcast:2 row_mask:0xf bank_mask:0xf
	v_mov_b32_dpp v137, v246 row_newbcast:3 row_mask:0xf bank_mask:0xf
	v_mov_b32_dpp v122, v246 row_newbcast:4 row_mask:0xf bank_mask:0xf
	v_mov_b32_dpp v123, v246 row_newbcast:5 row_mask:0xf bank_mask:0xf
	v_mov_b32_dpp v124, v246 row_newbcast:6 row_mask:0xf bank_mask:0xf
	v_mov_b32_dpp v125, v246 row_newbcast:7 row_mask:0xf bank_mask:0xf
	v_mov_b32_dpp v78, v246 row_newbcast:8 row_mask:0xf bank_mask:0xf
	v_mov_b32_dpp v79, v246 row_newbcast:9 row_mask:0xf bank_mask:0xf
	v_mov_b32_dpp v80, v246 row_newbcast:10 row_mask:0xf bank_mask:0xf
	v_mov_b32_dpp v81, v246 row_newbcast:11 row_mask:0xf bank_mask:0xf
	v_mov_b32_dpp v62, v246 row_newbcast:12 row_mask:0xf bank_mask:0xf
	v_mov_b32_dpp v63, v246 row_newbcast:13 row_mask:0xf bank_mask:0xf
	v_mov_b32_dpp v64, v246 row_newbcast:14 row_mask:0xf bank_mask:0xf
	v_mov_b32_dpp v65, v246 row_newbcast:15 row_mask:0xf bank_mask:0xf
	v_mov_b32_dpp v82, v247 row_newbcast:0 row_mask:0xf bank_mask:0xf
	v_mov_b32_dpp v83, v247 row_newbcast:1 row_mask:0xf bank_mask:0xf
	v_mov_b32_dpp v84, v247 row_newbcast:2 row_mask:0xf bank_mask:0xf
	v_mov_b32_dpp v85, v247 row_newbcast:3 row_mask:0xf bank_mask:0xf
	v_mov_b32_dpp v66, v247 row_newbcast:4 row_mask:0xf bank_mask:0xf
	v_mov_b32_dpp v67, v247 row_newbcast:5 row_mask:0xf bank_mask:0xf
	v_mov_b32_dpp v68, v247 row_newbcast:6 row_mask:0xf bank_mask:0xf
	v_mov_b32_dpp v69, v247 row_newbcast:7 row_mask:0xf bank_mask:0xf
	v_add_u32_e32 v154, -1, v213
	v_and_b32_e32 v155, 64, v213
	v_cmp_lt_i32_e32 vcc, v154, v155
	s_nop 1
	v_cndmask_b32_e32 v154, v154, v213, vcc
	v_lshlrev_b32_e32 v157, 2, v154
	s_nop 1
	v_mov_b32_dpp v166, v26 row_shr:1 row_mask:0xf bank_mask:0xf
	v_mov_b32_dpp v158, v22 row_shr:1 row_mask:0xf bank_mask:0xf
	v_mov_b32_dpp v167, v27 row_shr:1 row_mask:0xf bank_mask:0xf
	v_mov_b32_dpp v159, v23 row_shr:1 row_mask:0xf bank_mask:0xf
	v_mov_b32_dpp v168, v28 row_shr:1 row_mask:0xf bank_mask:0xf
	v_mov_b32_dpp v160, v24 row_shr:1 row_mask:0xf bank_mask:0xf
	v_mov_b32_dpp v169, v29 row_shr:1 row_mask:0xf bank_mask:0xf
	v_mov_b32_dpp v161, v25 row_shr:1 row_mask:0xf bank_mask:0xf
	v_mov_b32_dpp v162, v10 row_shr:1 row_mask:0xf bank_mask:0xf
	v_mov_b32_dpp v154, v6 row_shr:1 row_mask:0xf bank_mask:0xf
	v_mov_b32_dpp v163, v11 row_shr:1 row_mask:0xf bank_mask:0xf
	v_mov_b32_dpp v155, v7 row_shr:1 row_mask:0xf bank_mask:0xf
	v_mov_b32_dpp v164, v12 row_shr:1 row_mask:0xf bank_mask:0xf
	v_mov_b32_dpp v156, v8 row_shr:1 row_mask:0xf bank_mask:0xf
	v_mov_b32_dpp v165, v13 row_shr:1 row_mask:0xf bank_mask:0xf
	v_mov_b32_dpp v157, v9 row_shr:1 row_mask:0xf bank_mask:0xf
	s_and_saveexec_b64 s[4:5], s[54:55]
	s_cbranch_execz .LBB0_33
	ds_write_b128 v231, v[26:29]
	ds_write_b128 v231, v[22:25] offset:32
	ds_write_b128 v231, v[10:13] offset:16
	ds_write_b128 v231, v[6:9] offset:48

; #define LAS __attribute__((address_space(3)))
;     DEV bool operator()(f32x4 (&acc)[2][2][4][2], const Unit& u, int wr, int wc, int fr, int fq) const {
;     ...
;         if (!act_mode && u.pn < 16) {
;             const int ch0 = u.pn * 64 + wc * 16 + (fq & 1) * 8 + (fq >> 1) * 4, chb = u.pn * 64 + wc * 16 + (fq & 1) * 8, up = fq >> 1;
;             f32x4 w[3];
; #pragma unroll
;             for (int k = 0; k < 3; ++k) w[k] = *(const f32x4*)(cwa + k * 1024 + ch0);
;             f32x4 xp[8];
; #pragma unroll
;             for (int i = 0; i < 8; ++i) xp[i] = acc[i >> 2][0][i & 3][1] * acc[i >> 2][1][i & 3][0];
;             f32x4 p6, p7;
; #pragma unroll
;             for (int c = 0; c < 4; ++c) { p6[c] = __shfl_up(xp[6][c], 1); p7[c] = __shfl_up(xp[7][c], 1); }
;             LAS f32x4* EX = (LAS f32x4*)ex + (wc * 4 + fq) * 2;
;             if (wr == 0 && fr == 15) { EX[0] = xp[6]; EX[1] = xp[7]; }
.LBB0_436:
	s_and_b64 vcc, exec, s[4:5]
	s_cbranch_vccz .LBB0_448
	v_lshl_or_b32 v196, s8, 6, v198
	v_or_b32_e32 v166, v196, v200
	v_ashrrev_i32_e32 v167, 31, v166
	v_add_u32_e32 v0, -1, v213
	v_and_b32_e32 v150, 64, v213
	v_mov_b32_dpp v130, v252 row_newbcast:0 row_mask:0xf bank_mask:0xf
	v_mov_b32_dpp v131, v252 row_newbcast:1 row_mask:0xf bank_mask:0xf
	v_mov_b32_dpp v132, v252 row_newbcast:2 row_mask:0xf bank_mask:0xf
	v_mov_b32_dpp v133, v252 row_newbcast:3 row_mask:0xf bank_mask:0xf
	v_mov_b32_dpp v134, v252 row_newbcast:4 row_mask:0xf bank_mask:0xf
	v_mov_b32_dpp v135, v252 row_newbcast:5 row_mask:0xf bank_mask:0xf
	v_mov_b32_dpp v136, v252 row_newbcast:6 row_mask:0xf bank_mask:0xf
	v_mov_b32_dpp v137, v252 row_newbcast:7 row_mask:0xf bank_mask:0xf
	v_mov_b32_dpp v138, v252 row_newbcast:8 row_mask:0xf bank_mask:0xf
	v_mov_b32_dpp v139, v252 row_newbcast:9 row_mask:0xf bank_mask:0xf
	v_mov_b32_dpp v140, v252 row_newbcast:10 row_mask:0xf bank_mask:0xf
	v_mov_b32_dpp v141, v252 row_newbcast:11 row_mask:0xf bank_mask:0xf
	v_cmp_lt_i32_e32 vcc, v0, v150
	v_pk_mul_f32 v[144:145], v[28:29], v[24:25]
	v_pk_mul_f32 v[142:143], v[26:27], v[22:23]
	v_cndmask_b32_e32 v0, v0, v213, vcc
	v_pk_mul_f32 v[148:149], v[12:13], v[8:9]
	v_pk_mul_f32 v[146:147], v[10:11], v[6:7]
	v_lshlrev_b32_e32 v0, 2, v0
	s_nop 1
	v_mov_b32_dpp v162, v142 row_shr:1 row_mask:0xf bank_mask:0xf
	v_mov_b32_dpp v158, v146 row_shr:1 row_mask:0xf bank_mask:0xf
	v_mov_b32_dpp v163, v143 row_shr:1 row_mask:0xf bank_mask:0xf
	v_mov_b32_dpp v159, v147 row_shr:1 row_mask:0xf bank_mask:0xf
	v_mov_b32_dpp v164, v144 row_shr:1 row_mask:0xf bank_mask:0xf
	v_mov_b32_dpp v160, v148 row_shr:1 row_mask:0xf bank_mask:0xf
	v_mov_b32_dpp v165, v145 row_shr:1 row_mask:0xf bank_mask:0xf
	v_mov_b32_dpp v161, v149 row_shr:1 row_mask:0xf bank_mask:0xf
	s_mov_b64 s[4:5], exec
	v_readlane_b32 s6, v255, 4
	v_readlane_b32 s7, v255, 5
	s_and_b64 s[6:7], s[4:5], s[6:7]
	s_mov_b64 exec, s[6:7]
	s_cbranch_execz .LBB0_439
	ds_write_b128 v204, v[142:145]
	ds_write_b128 v204, v[146:149] offset:16
